# w_in transposes: tile order swapped to column-tile-major so concurrent WGs write whole dst rows
# baseline (speedup 1.0000x reference)
.LBB0_34:
	s_and_b32 s0, s20, 31
	s_lshr_b32 s22, s20, 5
	s_lshl_b32 s22, s22, 8
	s_mul_i32 s4, s0, 0x3c00
	s_add_i32 s22, s22, s4
	s_add_i32 s22, s22, 0xfff58000
	s_mul_i32 s5, s0, 0xffffc400
	s_add_i32 s5, s22, s5
	s_add_i32 s6, s5, 0xa8000
	s_ashr_i32 s7, s6, 31
	s_lshl_b32 s4, s0, 6
	v_mov_b32_e32 v52, v1
	s_lshl_b64 s[6:7], s[6:7], 2
	s_add_u32 s6, s74, s6
	v_lshlrev_b32_e32 v4, 4, v52
	s_addc_u32 s7, s75, s7
	v_and_b32_e32 v4, 0x3f0, v4
	v_ashrrev_i32_e32 v38, 6, v52
	v_add_u32_e32 v53, 0x200, v52
	v_lshl_add_u64 v[34:35], s[6:7], 0, v[4:5]
	v_add_u32_e32 v4, s4, v38
	v_ashrrev_i32_e32 v40, 6, v53
	v_add_u32_e32 v54, 0x400, v52
	v_mad_i64_i32 v[6:7], s[6:7], v4, s19, v[34:35]
	v_add_u32_e32 v4, s4, v40
	v_ashrrev_i32_e32 v42, 6, v54
	v_add_u32_e32 v55, 0x600, v52
	v_mad_i64_i32 v[10:11], s[6:7], v4, s19, v[34:35]
	v_add_u32_e32 v4, s4, v42
	v_ashrrev_i32_e32 v44, 6, v55
	global_load_dwordx4 v[6:9], v[6:7], off
	s_nop 0
	global_load_dwordx4 v[10:13], v[10:11], off
	v_mad_i64_i32 v[14:15], s[6:7], v4, s19, v[34:35]
	v_add_u32_e32 v4, s4, v44
	v_mad_i64_i32 v[18:19], s[6:7], v4, s19, v[34:35]
	v_add_u32_e32 v4, 0x800, v52
	v_ashrrev_i32_e32 v46, 6, v4
	v_add_u32_e32 v4, s4, v46
	global_load_dwordx4 v[14:17], v[14:15], off
	s_nop 0
	global_load_dwordx4 v[18:21], v[18:19], off
	v_mad_i64_i32 v[22:23], s[6:7], v4, s19, v[34:35]
	v_add_u32_e32 v4, 0xa00, v52
	v_ashrrev_i32_e32 v48, 6, v4
	v_add_u32_e32 v4, s4, v48
	v_mad_i64_i32 v[26:27], s[6:7], v4, s19, v[34:35]
	global_load_dwordx4 v[22:25], v[22:23], off
	s_nop 0
	global_load_dwordx4 v[26:29], v[26:27], off
	v_add_u32_e32 v4, 0xc00, v52
	v_ashrrev_i32_e32 v50, 6, v4
	v_add_u32_e32 v4, s4, v50
	v_mad_i64_i32 v[30:31], s[6:7], v4, s19, v[34:35]
	v_add_u32_e32 v4, 0xe00, v52
	v_ashrrev_i32_e32 v56, 6, v4
	v_add_u32_e32 v4, s4, v56
	v_lshlrev_b32_e32 v57, 3, v52
	v_mad_i64_i32 v[34:35], s[6:7], v4, s19, v[34:35]
	v_and_b32_e32 v4, 0x1f8, v57
	global_load_dwordx4 v[30:33], v[30:31], off
	v_mad_u64_u32 v[38:39], s[6:7], v38, s17, v[4:5]
	global_load_dwordx4 v[34:37], v[34:35], off
	v_mad_u64_u32 v[40:41], s[6:7], v40, s17, v[4:5]
	v_mad_u64_u32 v[42:43], s[6:7], v42, s17, v[4:5]
	v_mad_u64_u32 v[44:45], s[6:7], v44, s17, v[4:5]
	v_mad_u64_u32 v[46:47], s[6:7], v46, s17, v[4:5]
	v_mad_u64_u32 v[48:49], s[6:7], v48, s17, v[4:5]
	v_mad_u64_u32 v[50:51], s[6:7], v50, s17, v[4:5]
	s_ashr_i32 s5, s4, 31
	s_lshl_b64 s[4:5], s[4:5], 1
	s_add_u32 s4, s94, s4
	s_addc_u32 s5, s95, s5
	s_mulk_i32 s0, 0x3c00
	s_waitcnt vmcnt(7)
	v_cvt_pk_bf16_f32 v6, v6, v7
	ds_write_b32 v38, v6
	v_cvt_pk_bf16_f32 v6, v8, v9
	ds_write_b32 v38, v6 offset:4
	s_waitcnt vmcnt(6)
	v_cvt_pk_bf16_f32 v6, v10, v11
	ds_write_b32 v40, v6
	v_cvt_pk_bf16_f32 v6, v12, v13
	ds_write_b32 v40, v6 offset:4
	s_waitcnt vmcnt(5)
	v_cvt_pk_bf16_f32 v6, v14, v15
	ds_write_b32 v42, v6
	v_cvt_pk_bf16_f32 v6, v16, v17
	ds_write_b32 v42, v6 offset:4
	s_waitcnt vmcnt(4)
	v_cvt_pk_bf16_f32 v6, v18, v19
	ds_write_b32 v44, v6
	v_cvt_pk_bf16_f32 v6, v20, v21
	ds_write_b32 v44, v6 offset:4
	s_waitcnt vmcnt(3)
	v_cvt_pk_bf16_f32 v6, v22, v23
	ds_write_b32 v46, v6
	v_cvt_pk_bf16_f32 v6, v24, v25
	ds_write_b32 v46, v6 offset:4
	s_waitcnt vmcnt(2)
	v_cvt_pk_bf16_f32 v6, v26, v27
	ds_write_b32 v48, v6
	v_cvt_pk_bf16_f32 v6, v28, v29
	ds_write_b32 v48, v6 offset:4
	s_waitcnt vmcnt(1)
	v_cvt_pk_bf16_f32 v6, v30, v31
	ds_write_b32 v50, v6
	v_cvt_pk_bf16_f32 v6, v32, v33
	ds_write_b32 v50, v6 offset:4
	v_mad_u64_u32 v[6:7], s[6:7], v56, s17, v[4:5]
	s_waitcnt vmcnt(0)
	v_cvt_pk_bf16_f32 v8, v34, v35
	ds_write_b32 v6, v8
	v_cvt_pk_bf16_f32 v4, v36, v37
	ds_write_b32 v6, v4 offset:4
	v_and_b32_e32 v4, 56, v57
	v_mul_u32_u24_e32 v14, 0x204, v4
	v_ashrrev_i32_e32 v12, 3, v52
	v_lshl_add_u32 v6, v12, 1, v14
	s_waitcnt lgkmcnt(0)
	s_barrier
	ds_read_u16 v13, v6
	ds_read_u16 v15, v6 offset:516
	ds_read_u16 v7, v6 offset:1032
	ds_read_u16 v16, v6 offset:1548
	ds_read_u16 v8, v6 offset:2064
	ds_read_u16 v17, v6 offset:2580
	ds_read_u16 v9, v6 offset:3096
	ds_read_u16 v6, v6 offset:3612
	v_lshlrev_b32_e32 v4, 1, v4
	v_lshl_add_u64 v[10:11], s[4:5], 0, v[4:5]
	v_subrev_u32_e32 v4, s0, v12
	v_add_u32_e32 v4, s22, v4
	v_add_u32_e32 v12, 0xa8000, v4
	v_ashrrev_i32_e32 v4, 3, v53
	s_waitcnt lgkmcnt(0)
	v_perm_b32 v9, v6, v9, s18
	v_perm_b32 v6, v15, v13, s18
	v_lshl_add_u32 v13, v4, 1, v14
	v_perm_b32 v8, v17, v8, s18
	v_perm_b32 v7, v16, v7, s18
	ds_read_u16 v15, v13
	ds_read_u16 v16, v13 offset:516
	ds_read_u16 v17, v13 offset:1032
	ds_read_u16 v18, v13 offset:1548
	ds_read_u16 v19, v13 offset:2064
	ds_read_u16 v20, v13 offset:2580
	ds_read_u16 v21, v13 offset:3096
	ds_read_u16 v22, v13 offset:3612
	v_ashrrev_i32_e32 v13, 31, v12
	v_lshlrev_b64 v[12:13], 12, v[12:13]
	v_subrev_u32_e32 v4, s0, v4
	v_lshl_add_u64 v[12:13], v[10:11], 0, v[12:13]
	v_add_u32_e32 v4, s22, v4
	global_store_dwordx4 v[12:13], v[6:9], off
	v_add_u32_e32 v12, 0xa8000, v4
	v_ashrrev_i32_e32 v4, 3, v54
	v_lshl_add_u32 v13, v4, 1, v14
	s_waitcnt lgkmcnt(0)
	v_perm_b32 v9, v22, v21, s18
	v_perm_b32 v8, v20, v19, s18
	v_perm_b32 v7, v18, v17, s18
	v_perm_b32 v6, v16, v15, s18
	ds_read_u16 v15, v13
	ds_read_u16 v16, v13 offset:516
	ds_read_u16 v17, v13 offset:1032
	ds_read_u16 v18, v13 offset:1548
	ds_read_u16 v19, v13 offset:2064
	ds_read_u16 v20, v13 offset:2580
	ds_read_u16 v21, v13 offset:3096
	ds_read_u16 v22, v13 offset:3612
	v_ashrrev_i32_e32 v13, 31, v12
	v_lshlrev_b64 v[12:13], 12, v[12:13]
	v_subrev_u32_e32 v4, s0, v4
	v_lshl_add_u64 v[12:13], v[10:11], 0, v[12:13]
	v_add_u32_e32 v4, s22, v4
	global_store_dwordx4 v[12:13], v[6:9], off
	v_add_u32_e32 v12, 0xa8000, v4
	v_ashrrev_i32_e32 v4, 3, v55
	v_lshl_add_u32 v13, v4, 1, v14
	s_waitcnt lgkmcnt(0)
	v_perm_b32 v9, v22, v21, s18
	v_perm_b32 v8, v20, v19, s18
	v_perm_b32 v7, v18, v17, s18
	v_perm_b32 v6, v16, v15, s18
	ds_read_u16 v14, v13
	ds_read_u16 v15, v13 offset:516
	ds_read_u16 v16, v13 offset:1032
	ds_read_u16 v17, v13 offset:1548
	ds_read_u16 v18, v13 offset:2064
	ds_read_u16 v19, v13 offset:2580
	ds_read_u16 v20, v13 offset:3096
	ds_read_u16 v21, v13 offset:3612
	v_ashrrev_i32_e32 v13, 31, v12
	v_lshlrev_b64 v[12:13], 12, v[12:13]
	v_subrev_u32_e32 v4, s0, v4
	v_lshl_add_u64 v[12:13], v[10:11], 0, v[12:13]
	v_add_u32_e32 v4, s22, v4
	global_store_dwordx4 v[12:13], v[6:9], off
	v_add_u32_e32 v12, 0xa8000, v4
	v_ashrrev_i32_e32 v13, 31, v12
	v_lshlrev_b64 v[12:13], 12, v[12:13]
	s_waitcnt lgkmcnt(0)
	v_perm_b32 v9, v21, v20, s18
	v_perm_b32 v8, v19, v18, s18
	v_perm_b32 v7, v17, v16, s18
	v_perm_b32 v6, v15, v14, s18
	v_lshl_add_u64 v[10:11], v[10:11], 0, v[12:13]
	global_store_dwordx4 v[10:11], v[6:9], off
	s_barrier
	s_branch .LBB0_23

.LBB0_88:
	s_and_b32 s6, s5, 31
	s_lshr_b32 s4, s5, 5
	s_lshl_b32 s4, s4, 8
	s_mul_i32 s1, s6, 0x3c00
	s_add_i32 s4, s4, s1
	s_mul_i32 s1, s6, 0xffffc400
	s_add_i32 s8, s4, s1
	s_ashr_i32 s9, s8, 31
	s_lshl_b32 s0, s6, 6
	v_mov_b32_e32 v7, v1
	s_lshl_b64 s[8:9], s[8:9], 2
	s_add_u32 s8, s17, s8
	v_lshlrev_b32_e32 v2, 4, v7
	v_add_u32_e32 v24, 0x800, v7
	s_addc_u32 s9, s20, s9
	v_and_b32_e32 v194, 0x3f0, v2
	v_ashrrev_i32_e32 v40, 6, v7
	v_ashrrev_i32_e32 v44, 6, v24
	v_lshl_add_u64 v[2:3], s[8:9], 0, v[194:195]
	v_add_u32_e32 v4, s0, v40
	v_add_u32_e32 v41, 0x200, v7
	v_add_u32_e32 v24, s0, v44
	v_add_u32_e32 v28, 0xa00, v7
	v_mad_i64_i32 v[4:5], s[8:9], v4, s25, v[2:3]
	v_ashrrev_i32_e32 v42, 6, v41
	v_mad_i64_i32 v[24:25], s[8:9], v24, s25, v[2:3]
	v_ashrrev_i32_e32 v45, 6, v28
	global_load_dwordx4 v[8:11], v[4:5], off
	v_add_u32_e32 v6, 0x400, v7
	global_load_dwordx4 v[24:27], v[24:25], off
	v_add_u32_e32 v4, s0, v42
	v_add_u32_e32 v28, s0, v45
	v_add_u32_e32 v32, 0xc00, v7
	v_mad_i64_i32 v[4:5], s[8:9], v4, s25, v[2:3]
	v_ashrrev_i32_e32 v43, 6, v6
	v_mad_i64_i32 v[28:29], s[8:9], v28, s25, v[2:3]
	v_ashrrev_i32_e32 v46, 6, v32
	global_load_dwordx4 v[12:15], v[4:5], off
	v_add_u32_e32 v32, s0, v46
	global_load_dwordx4 v[28:31], v[28:29], off
	v_add_u32_e32 v4, s0, v43
	v_mad_i64_i32 v[4:5], s[8:9], v4, s25, v[2:3]
	v_mad_i64_i32 v[32:33], s[8:9], v32, s25, v[2:3]
	global_load_dwordx4 v[16:19], v[4:5], off
	v_add_u32_e32 v36, 0xe00, v7
	global_load_dwordx4 v[32:35], v[32:33], off
	v_add_u32_e32 v4, 0x600, v7
	v_ashrrev_i32_e32 v5, 6, v4
	v_ashrrev_i32_e32 v47, 6, v36
	v_add_u32_e32 v20, s0, v5
	v_add_u32_e32 v36, s0, v47
	v_mad_i64_i32 v[20:21], s[8:9], v20, s25, v[2:3]
	v_mad_i64_i32 v[2:3], s[8:9], v36, s25, v[2:3]
	v_lshlrev_b32_e32 v48, 3, v7
	global_load_dwordx4 v[20:23], v[20:21], off
	v_ashrrev_i32_e32 v7, 3, v7
	global_load_dwordx4 v[36:39], v[2:3], off
	v_and_b32_e32 v2, 0x1f8, v48
	s_waitcnt vmcnt(0)
	v_cvt_pk_bf16_f32 v3, v8, v9
	s_ashr_i32 s1, s0, 31
	v_mad_u64_u32 v[8:9], s[8:9], v40, s33, v[2:3]
	ds_write_b32 v8, v3
	v_cvt_pk_bf16_f32 v3, v10, v11
	ds_write_b32 v8, v3 offset:4
	s_waitcnt vmcnt(5)
	v_cvt_pk_bf16_f32 v3, v12, v13
	s_mulk_i32 s6, 0x3c00
	v_mad_u64_u32 v[8:9], s[8:9], v42, s33, v[2:3]
	ds_write_b32 v8, v3
	v_cvt_pk_bf16_f32 v3, v14, v15
	ds_write_b32 v8, v3 offset:4
	s_waitcnt vmcnt(3)
	v_cvt_pk_bf16_f32 v3, v16, v17
	s_lshl_b64 s[0:1], s[0:1], 1
	v_mad_u64_u32 v[8:9], s[8:9], v43, s33, v[2:3]
	ds_write_b32 v8, v3
	v_cvt_pk_bf16_f32 v3, v18, v19
	ds_write_b32 v8, v3 offset:4
	s_waitcnt vmcnt(1)
	v_cvt_pk_bf16_f32 v3, v20, v21
	s_add_u32 s0, s94, s0
	v_mad_u64_u32 v[8:9], s[8:9], v5, s33, v[2:3]
	ds_write_b32 v8, v3
	v_cvt_pk_bf16_f32 v3, v22, v23
	ds_write_b32 v8, v3 offset:4
	v_cvt_pk_bf16_f32 v3, v24, v25
	s_addc_u32 s1, s95, s1
	v_mad_u64_u32 v[8:9], s[8:9], v44, s33, v[2:3]
	ds_write_b32 v8, v3
	v_cvt_pk_bf16_f32 v3, v26, v27
	ds_write_b32 v8, v3 offset:4
	v_cvt_pk_bf16_f32 v3, v28, v29
	s_add_i32 s5, s5, s30
	v_mad_u64_u32 v[8:9], s[8:9], v45, s33, v[2:3]
	ds_write_b32 v8, v3
	v_cvt_pk_bf16_f32 v3, v30, v31
	ds_write_b32 v8, v3 offset:4
	v_cvt_pk_bf16_f32 v3, v32, v33
	s_nop 0
	v_mad_u64_u32 v[8:9], s[8:9], v46, s33, v[2:3]
	ds_write_b32 v8, v3
	v_cvt_pk_bf16_f32 v3, v34, v35
	ds_write_b32 v8, v3 offset:4
	s_waitcnt vmcnt(0)
	v_cvt_pk_bf16_f32 v5, v36, v37
	v_mad_u64_u32 v[2:3], s[8:9], v47, s33, v[2:3]
	ds_write_b32 v2, v5
	v_and_b32_e32 v5, 56, v48
	v_lshlrev_b32_e32 v194, 1, v5
	v_mul_u32_u24_e32 v5, 0x204, v5
	v_lshl_add_u32 v8, v7, 1, v5
	v_cvt_pk_bf16_f32 v3, v38, v39
	ds_write_b32 v2, v3 offset:4
	s_waitcnt lgkmcnt(0)
	s_barrier
	ds_read_u16 v12, v8
	ds_read_u16 v13, v8 offset:516
	ds_read_u16 v9, v8 offset:1032
	ds_read_u16 v14, v8 offset:1548
	ds_read_u16 v10, v8 offset:2064
	ds_read_u16 v15, v8 offset:2580
	ds_read_u16 v11, v8 offset:3096
	ds_read_u16 v8, v8 offset:3612
	v_subrev_u32_e32 v7, s6, v7
	v_lshl_add_u64 v[2:3], s[0:1], 0, v[194:195]
	s_waitcnt lgkmcnt(2)
	v_perm_b32 v10, v15, v10, s34
	v_perm_b32 v9, v14, v9, s34
	s_waitcnt lgkmcnt(0)
	v_perm_b32 v11, v8, v11, s34
	v_perm_b32 v8, v13, v12, s34
	v_add_u32_e32 v12, s4, v7
	v_ashrrev_i32_e32 v13, 31, v12
	v_lshlrev_b64 v[12:13], 12, v[12:13]
	v_lshl_add_u64 v[12:13], v[2:3], 0, v[12:13]
	v_ashrrev_i32_e32 v7, 3, v41
	global_store_dwordx4 v[12:13], v[8:11], off
	s_nop 1
	v_lshl_add_u32 v8, v7, 1, v5
	ds_read_u16 v12, v8
	ds_read_u16 v13, v8 offset:516
	ds_read_u16 v9, v8 offset:1032
	ds_read_u16 v14, v8 offset:1548
	ds_read_u16 v10, v8 offset:2064
	ds_read_u16 v15, v8 offset:2580
	ds_read_u16 v11, v8 offset:3096
	ds_read_u16 v8, v8 offset:3612
	v_subrev_u32_e32 v7, s6, v7
	s_waitcnt lgkmcnt(4)
	v_perm_b32 v9, v14, v9, s34
	s_waitcnt lgkmcnt(2)
	v_perm_b32 v10, v15, v10, s34
	s_waitcnt lgkmcnt(0)
	v_perm_b32 v11, v8, v11, s34
	v_perm_b32 v8, v13, v12, s34
	v_add_u32_e32 v12, s4, v7
	v_ashrrev_i32_e32 v13, 31, v12
	v_lshlrev_b64 v[12:13], 12, v[12:13]
	v_lshl_add_u64 v[12:13], v[2:3], 0, v[12:13]
	global_store_dwordx4 v[12:13], v[8:11], off
	s_nop 1
	v_ashrrev_i32_e32 v10, 3, v6
	v_lshl_add_u32 v6, v10, 1, v5
	ds_read_u16 v11, v6
	ds_read_u16 v12, v6 offset:516
	ds_read_u16 v7, v6 offset:1032
	ds_read_u16 v13, v6 offset:1548
	ds_read_u16 v8, v6 offset:2064
	ds_read_u16 v14, v6 offset:2580
	ds_read_u16 v9, v6 offset:3096
	ds_read_u16 v6, v6 offset:3612
	v_subrev_u32_e32 v10, s6, v10
	v_add_u32_e32 v10, s4, v10
	s_waitcnt lgkmcnt(2)
	v_perm_b32 v8, v14, v8, s34
	v_perm_b32 v7, v13, v7, s34
	s_waitcnt lgkmcnt(0)
	v_perm_b32 v9, v6, v9, s34
	v_perm_b32 v6, v12, v11, s34
	v_ashrrev_i32_e32 v11, 31, v10
	v_lshlrev_b64 v[10:11], 12, v[10:11]
	v_lshl_add_u64 v[10:11], v[2:3], 0, v[10:11]
	global_store_dwordx4 v[10:11], v[6:9], off
	s_nop 1
	v_ashrrev_i32_e32 v8, 3, v4
	v_lshl_add_u32 v4, v8, 1, v5
	ds_read_u16 v9, v4
	ds_read_u16 v10, v4 offset:516
	ds_read_u16 v5, v4 offset:1032
	ds_read_u16 v11, v4 offset:1548
	ds_read_u16 v6, v4 offset:2064
	ds_read_u16 v12, v4 offset:2580
	ds_read_u16 v7, v4 offset:3096
	ds_read_u16 v4, v4 offset:3612
	v_subrev_u32_e32 v8, s6, v8
	v_add_u32_e32 v8, s4, v8
	s_add_i32 s4, s4, s24
	s_waitcnt lgkmcnt(2)
	v_perm_b32 v6, v12, v6, s34
	s_waitcnt lgkmcnt(0)
	v_perm_b32 v7, v4, v7, s34
	v_perm_b32 v4, v10, v9, s34
	v_ashrrev_i32_e32 v9, 31, v8
	v_lshlrev_b64 v[8:9], 12, v[8:9]
	v_perm_b32 v5, v11, v5, s34
	v_lshl_add_u64 v[2:3], v[2:3], 0, v[8:9]
	s_cmpk_lt_i32 s5, 0x780
	global_store_dwordx4 v[2:3], v[4:7], off
	s_barrier
	s_cbranch_scc1 .LBB0_88
